# out_proj epilogue rewritten: residual kept f32 in accumulators, row sums exchanged inside 8-WG panel group, final RMSNorm fused; grid barrier + final phase removed
# speedup vs baseline: 1.0114x; 1.0114x over previous
; __device__ __forceinline__ f32x4 ld_nt(const float* p) { return __builtin_nontemporal_load((const f32x4*)p); }
; __device__ __forceinline__ u32x4 pack8h(const f32x4 v0, const f32x4 v1) { u32x4 w; w.x = pk_h16(v0[0], v0[1]); w.y = pk_h16(v0[2], v0[3]); w.z = pk_h16(v1[0], v1[1]); w.w = pk_h16(v1[2], v1[3]); return w; }
;     __device__ __forceinline__ void operator()(AccRef acc, const Unit& u, int wr, int wc, int fr, int fq) const {
;         int row0 = u.pm * 256 + wr * 64 + fr; asm volatile("" : "+v"(row0)); int col0 = u.pn * 256 + wc * 32 + 8 * fq; asm volatile("" : "+v"(col0));
;         const float* gate = mod + (size_t)(u.pm >= 32 ? 1 : 0) * 3 * D + 2 * D + col0;
;         f32x4 gv[2][2];
; #pragma unroll
;         for (int bj = 0; bj < 2; ++bj)
; #pragma unroll
;             for (int n = 0; n < 2; ++n) gv[bj][n] = *(const f32x4*)(gate + bj * HALF + n * 4);
; #pragma unroll
;         for (int ai = 0; ai < 2; ++ai)
; #pragma unroll
;             for (int mp = 0; mp < 2; ++mp) { f32x4 xv[2][2][2];
; #pragma unroll
;                 for (int mm = 0; mm < 2; ++mm)
; #pragma unroll
;                     for (int bj = 0; bj < 2; ++bj)
; #pragma unroll
;                         for (int n = 0; n < 2; ++n) xv[mm][bj][n] = ld_nt(x + (size_t)(row0 + ai * HALF + (mp * 2 + mm) * 16) * D + col0 + bj * HALF + n * 4);
;                 __builtin_amdgcn_sched_barrier(0);
; #pragma unroll
;                 for (int mm = 0; mm < 2; ++mm) { const int m = mp * 2 + mm; const int row = row0 + ai * HALF + m * 16; const size_t o = (size_t)row * D + col0; float ss = 0.f;
; #pragma unroll
;                     for (int bj = 0; bj < 2; ++bj) { const f32x4 r0 = xv[mm][bj][0] + gv[bj][0] * acc[ai][bj][m][0], r1 = xv[mm][bj][1] + gv[bj][1] * acc[ai][bj][m][1];
;                         *(u32x4*)(xo + o + bj * HALF) = pack8h(r0, r1);
;                         ss += ((r0[0] * r0[0] + r0[1] * r0[1]) + (r0[2] * r0[2] + r0[3] * r0[3])) + ((r1[0] * r1[0] + r1[1] * r1[1]) + (r1[2] * r1[2] + r1[3] * r1[3])); }
;                     ss += __shfl_xor(ss, 16); ss += __shfl_xor(ss, 32);
;                     if (fq == 0) rowss[(size_t)row * 32 + u.pn * 4 + wc] = ss; } }
.LBB0_1154:
	v_lshl_add_u32 v172, s58, 8, v178
	v_lshl_or_b32 v170, s22, 8, v180
	v_readlane_b32 s80, v254, 2
	v_readlane_b32 s81, v254, 3
	v_lshlrev_b32_e32 v173, 13, v172
	v_lshlrev_b32_e32 v187, 7, v172
	v_lshlrev_b32_e32 v171, 2, v170
	v_lshl_add_u32 v173, v170, 2, v173
	s_cmp_gt_i32 s58, 31
	s_cselect_b32 s18, 0x6000, 0
	s_add_u32 s92, s50, s18
	s_addc_u32 s93, s51, 0
	s_add_u32 s92, s92, 0x104000
	s_addc_u32 s93, s93, 0
	s_lshl_b32 s18, s22, 2
	s_add_u32 s18, s18, s72
	s_lshl_b32 s18, s18, 2
	s_add_u32 s88, s26, s18
	s_addc_u32 s89, s27, 0
	v_xor_b32_e32 v186, 16, v184
	v_xor_b32_e32 v185, 32, v184
	v_lshrrev_b32_e32 v174, 4, v184
	v_lshlrev_b32_e32 v186, 2, v186
	v_lshlrev_b32_e32 v185, 2, v185
	v_lshl_add_u32 v174, v174, 5, v187
	global_load_dwordx4 v[120:123], v171, s[92:93]
	global_load_dwordx4 v[112:115], v171, s[92:93] offset:16
	global_load_dwordx4 v[108:111], v171, s[92:93] offset:512
	global_load_dwordx4 v[104:107], v171, s[92:93] offset:528
	global_load_dwordx4 v[144:147], v171, s[46:47]
	global_load_dwordx4 v[148:151], v171, s[46:47] offset:16
	global_load_dwordx4 v[152:155], v171, s[46:47] offset:512
	global_load_dwordx4 v[156:159], v171, s[46:47] offset:528
	s_mov_b64 s[84:85], s[80:81]
	global_load_dwordx4 v[188:191], v173, s[84:85] nt
	global_load_dwordx4 v[192:195], v173, s[84:85] offset:16 nt
	global_load_dwordx4 v[196:199], v173, s[84:85] offset:512 nt
	global_load_dwordx4 v[200:203], v173, s[84:85] offset:528 nt
	s_add_u32 s84, s80, 0x20000
	s_addc_u32 s85, s81, 0
	global_load_dwordx4 v[214:217], v173, s[84:85] nt
	global_load_dwordx4 v[218:221], v173, s[84:85] offset:16 nt
	global_load_dwordx4 v[222:225], v173, s[84:85] offset:512 nt
	global_load_dwordx4 v[226:229], v173, s[84:85] offset:528 nt
	s_add_u32 s84, s80, 0x40000
	s_addc_u32 s85, s81, 0
	global_load_dwordx4 v[230:233], v173, s[84:85] nt
	global_load_dwordx4 v[234:237], v173, s[84:85] offset:16 nt
	global_load_dwordx4 v[238:241], v173, s[84:85] offset:512 nt
	global_load_dwordx4 v[242:245], v173, s[84:85] offset:528 nt
	s_waitcnt vmcnt(8)
	v_pk_fma_f32 v[140:141], v[140:141], v[120:121], v[188:189]
	v_pk_fma_f32 v[142:143], v[142:143], v[122:123], v[190:191]
	v_pk_fma_f32 v[136:137], v[136:137], v[112:113], v[192:193]
	v_pk_fma_f32 v[138:139], v[138:139], v[114:115], v[194:195]
	v_pk_fma_f32 v[132:133], v[132:133], v[108:109], v[196:197]
	v_pk_fma_f32 v[134:135], v[134:135], v[110:111], v[198:199]
	v_pk_fma_f32 v[128:129], v[128:129], v[104:105], v[200:201]
	v_pk_fma_f32 v[130:131], v[130:131], v[106:107], v[202:203]
	s_add_u32 s84, s80, 0x60000
	s_addc_u32 s85, s81, 0
	global_load_dwordx4 v[188:191], v173, s[84:85] nt
	global_load_dwordx4 v[192:195], v173, s[84:85] offset:16 nt
	global_load_dwordx4 v[196:199], v173, s[84:85] offset:512 nt
	global_load_dwordx4 v[200:203], v173, s[84:85] offset:528 nt
	v_pk_mul_f32 v[176:177], v[140:141], v[140:141]
	v_pk_fma_f32 v[176:177], v[142:143], v[142:143], v[176:177]
	v_pk_fma_f32 v[176:177], v[136:137], v[136:137], v[176:177]
	v_pk_fma_f32 v[176:177], v[138:139], v[138:139], v[176:177]
	v_pk_fma_f32 v[176:177], v[132:133], v[132:133], v[176:177]
	v_pk_fma_f32 v[176:177], v[134:135], v[134:135], v[176:177]
	v_pk_fma_f32 v[176:177], v[128:129], v[128:129], v[176:177]
	v_pk_fma_f32 v[176:177], v[130:131], v[130:131], v[176:177]
	v_add_f32_e32 v204, v176, v177
	s_waitcnt vmcnt(8)
	v_pk_fma_f32 v[124:125], v[124:125], v[120:121], v[214:215]
	v_pk_fma_f32 v[126:127], v[126:127], v[122:123], v[216:217]
	v_pk_fma_f32 v[116:117], v[116:117], v[112:113], v[218:219]
	v_pk_fma_f32 v[118:119], v[118:119], v[114:115], v[220:221]
	v_pk_fma_f32 v[100:101], v[100:101], v[108:109], v[222:223]
	v_pk_fma_f32 v[102:103], v[102:103], v[110:111], v[224:225]
	v_pk_fma_f32 v[96:97], v[96:97], v[104:105], v[226:227]
	v_pk_fma_f32 v[98:99], v[98:99], v[106:107], v[228:229]
	s_add_u32 s84, s80, 0x100000
	s_addc_u32 s85, s81, 0
	global_load_dwordx4 v[214:217], v173, s[84:85] nt
	global_load_dwordx4 v[218:221], v173, s[84:85] offset:16 nt
	global_load_dwordx4 v[222:225], v173, s[84:85] offset:512 nt
	global_load_dwordx4 v[226:229], v173, s[84:85] offset:528 nt
	v_pk_mul_f32 v[176:177], v[124:125], v[124:125]
	v_pk_fma_f32 v[176:177], v[126:127], v[126:127], v[176:177]
	v_pk_fma_f32 v[176:177], v[116:117], v[116:117], v[176:177]
	v_pk_fma_f32 v[176:177], v[118:119], v[118:119], v[176:177]
	v_pk_fma_f32 v[176:177], v[100:101], v[100:101], v[176:177]
	v_pk_fma_f32 v[176:177], v[102:103], v[102:103], v[176:177]
	v_pk_fma_f32 v[176:177], v[96:97], v[96:97], v[176:177]
	v_pk_fma_f32 v[176:177], v[98:99], v[98:99], v[176:177]
	v_add_f32_e32 v205, v176, v177
	s_waitcnt vmcnt(8)
	v_pk_fma_f32 v[92:93], v[92:93], v[120:121], v[230:231]
	v_pk_fma_f32 v[94:95], v[94:95], v[122:123], v[232:233]
	v_pk_fma_f32 v[88:89], v[88:89], v[112:113], v[234:235]
	v_pk_fma_f32 v[90:91], v[90:91], v[114:115], v[236:237]
	v_pk_fma_f32 v[84:85], v[84:85], v[108:109], v[238:239]
	v_pk_fma_f32 v[86:87], v[86:87], v[110:111], v[240:241]
	v_pk_fma_f32 v[80:81], v[80:81], v[104:105], v[242:243]
	v_pk_fma_f32 v[82:83], v[82:83], v[106:107], v[244:245]
	s_add_u32 s84, s80, 0x120000
	s_addc_u32 s85, s81, 0
	global_load_dwordx4 v[230:233], v173, s[84:85] nt
	global_load_dwordx4 v[234:237], v173, s[84:85] offset:16 nt
	global_load_dwordx4 v[238:241], v173, s[84:85] offset:512 nt
	global_load_dwordx4 v[242:245], v173, s[84:85] offset:528 nt
	v_pk_mul_f32 v[176:177], v[92:93], v[92:93]
	v_pk_fma_f32 v[176:177], v[94:95], v[94:95], v[176:177]
	v_pk_fma_f32 v[176:177], v[88:89], v[88:89], v[176:177]
	v_pk_fma_f32 v[176:177], v[90:91], v[90:91], v[176:177]
	v_pk_fma_f32 v[176:177], v[84:85], v[84:85], v[176:177]
	v_pk_fma_f32 v[176:177], v[86:87], v[86:87], v[176:177]
	v_pk_fma_f32 v[176:177], v[80:81], v[80:81], v[176:177]
	v_pk_fma_f32 v[176:177], v[82:83], v[82:83], v[176:177]
	v_add_f32_e32 v206, v176, v177
	s_waitcnt vmcnt(8)
; __device__ __forceinline__ u32x4 pack8h(const f32x4 v0, const f32x4 v1) { u32x4 w; w.x = pk_h16(v0[0], v0[1]); w.y = pk_h16(v0[2], v0[3]); w.z = pk_h16(v1[0], v1[1]); w.w = pk_h16(v1[2], v1[3]); return w; }
;     __device__ __forceinline__ void operator()(AccRef acc, const Unit& u, int wr, int wc, int fr, int fq) const {
;     ...
;                 for (int mm = 0; mm < 2; ++mm) { const int m = mp * 2 + mm; const int row = row0 + ai * HALF + m * 16; const size_t o = (size_t)row * D + col0; float ss = 0.f;
; #pragma unroll
;                     for (int bj = 0; bj < 2; ++bj) { const f32x4 r0 = xv[mm][bj][0] + gv[bj][0] * acc[ai][bj][m][0], r1 = xv[mm][bj][1] + gv[bj][1] * acc[ai][bj][m][1];
;                         *(u32x4*)(xo + o + bj * HALF) = pack8h(r0, r1);
;                         ss += ((r0[0] * r0[0] + r0[1] * r0[1]) + (r0[2] * r0[2] + r0[3] * r0[3])) + ((r1[0] * r1[0] + r1[1] * r1[1]) + (r1[2] * r1[2] + r1[3] * r1[3])); }
;                     ss += __shfl_xor(ss, 16); ss += __shfl_xor(ss, 32);
	v_pk_fma_f32 v[76:77], v[76:77], v[120:121], v[188:189]
	v_pk_fma_f32 v[78:79], v[78:79], v[122:123], v[190:191]
	v_pk_fma_f32 v[72:73], v[72:73], v[112:113], v[192:193]
	v_pk_fma_f32 v[74:75], v[74:75], v[114:115], v[194:195]
	v_pk_fma_f32 v[68:69], v[68:69], v[108:109], v[196:197]
	v_pk_fma_f32 v[70:71], v[70:71], v[110:111], v[198:199]
	v_pk_fma_f32 v[64:65], v[64:65], v[104:105], v[200:201]
	v_pk_fma_f32 v[66:67], v[66:67], v[106:107], v[202:203]
	s_add_u32 s84, s80, 0x140000
	s_addc_u32 s85, s81, 0
	global_load_dwordx4 v[188:191], v173, s[84:85] nt
	global_load_dwordx4 v[192:195], v173, s[84:85] offset:16 nt
	global_load_dwordx4 v[196:199], v173, s[84:85] offset:512 nt
	global_load_dwordx4 v[200:203], v173, s[84:85] offset:528 nt
	v_pk_mul_f32 v[176:177], v[76:77], v[76:77]
	v_pk_fma_f32 v[176:177], v[78:79], v[78:79], v[176:177]
	v_pk_fma_f32 v[176:177], v[72:73], v[72:73], v[176:177]
	v_pk_fma_f32 v[176:177], v[74:75], v[74:75], v[176:177]
	v_pk_fma_f32 v[176:177], v[68:69], v[68:69], v[176:177]
	v_pk_fma_f32 v[176:177], v[70:71], v[70:71], v[176:177]
	v_pk_fma_f32 v[176:177], v[64:65], v[64:65], v[176:177]
	v_pk_fma_f32 v[176:177], v[66:67], v[66:67], v[176:177]
	v_add_f32_e32 v207, v176, v177
	s_waitcnt vmcnt(8)
	v_pk_fma_f32 v[60:61], v[60:61], v[120:121], v[214:215]
	v_pk_fma_f32 v[62:63], v[62:63], v[122:123], v[216:217]
	v_pk_fma_f32 v[56:57], v[56:57], v[112:113], v[218:219]
	v_pk_fma_f32 v[58:59], v[58:59], v[114:115], v[220:221]
	v_pk_fma_f32 v[52:53], v[52:53], v[108:109], v[222:223]
	v_pk_fma_f32 v[54:55], v[54:55], v[110:111], v[224:225]
	v_pk_fma_f32 v[48:49], v[48:49], v[104:105], v[226:227]
	v_pk_fma_f32 v[50:51], v[50:51], v[106:107], v[228:229]
	s_add_u32 s84, s80, 0x160000
	s_addc_u32 s85, s81, 0
	global_load_dwordx4 v[214:217], v173, s[84:85] nt
	global_load_dwordx4 v[218:221], v173, s[84:85] offset:16 nt
	global_load_dwordx4 v[222:225], v173, s[84:85] offset:512 nt
	global_load_dwordx4 v[226:229], v173, s[84:85] offset:528 nt
	v_pk_mul_f32 v[176:177], v[60:61], v[60:61]
	v_pk_fma_f32 v[176:177], v[62:63], v[62:63], v[176:177]
	v_pk_fma_f32 v[176:177], v[56:57], v[56:57], v[176:177]
	v_pk_fma_f32 v[176:177], v[58:59], v[58:59], v[176:177]
	v_pk_fma_f32 v[176:177], v[52:53], v[52:53], v[176:177]
	v_pk_fma_f32 v[176:177], v[54:55], v[54:55], v[176:177]
	v_pk_fma_f32 v[176:177], v[48:49], v[48:49], v[176:177]
	v_pk_fma_f32 v[176:177], v[50:51], v[50:51], v[176:177]
	v_add_f32_e32 v208, v176, v177
	s_waitcnt vmcnt(8)
	v_pk_fma_f32 v[44:45], v[44:45], v[120:121], v[230:231]
	v_pk_fma_f32 v[46:47], v[46:47], v[122:123], v[232:233]
	v_pk_fma_f32 v[40:41], v[40:41], v[112:113], v[234:235]
	v_pk_fma_f32 v[42:43], v[42:43], v[114:115], v[236:237]
	v_pk_fma_f32 v[36:37], v[36:37], v[108:109], v[238:239]
	v_pk_fma_f32 v[38:39], v[38:39], v[110:111], v[240:241]
	v_pk_fma_f32 v[32:33], v[32:33], v[104:105], v[242:243]
	v_pk_fma_f32 v[34:35], v[34:35], v[106:107], v[244:245]
	v_pk_mul_f32 v[176:177], v[44:45], v[44:45]
	v_pk_fma_f32 v[176:177], v[46:47], v[46:47], v[176:177]
	v_pk_fma_f32 v[176:177], v[40:41], v[40:41], v[176:177]
	v_pk_fma_f32 v[176:177], v[42:43], v[42:43], v[176:177]
	v_pk_fma_f32 v[176:177], v[36:37], v[36:37], v[176:177]
	v_pk_fma_f32 v[176:177], v[38:39], v[38:39], v[176:177]
	v_pk_fma_f32 v[176:177], v[32:33], v[32:33], v[176:177]
	v_pk_fma_f32 v[176:177], v[34:35], v[34:35], v[176:177]
	v_add_f32_e32 v209, v176, v177
	s_waitcnt vmcnt(4)
	v_pk_fma_f32 v[28:29], v[28:29], v[120:121], v[188:189]
	v_pk_fma_f32 v[30:31], v[30:31], v[122:123], v[190:191]
	v_pk_fma_f32 v[24:25], v[24:25], v[112:113], v[192:193]
	v_pk_fma_f32 v[26:27], v[26:27], v[114:115], v[194:195]
	v_pk_fma_f32 v[20:21], v[20:21], v[108:109], v[196:197]
	v_pk_fma_f32 v[22:23], v[22:23], v[110:111], v[198:199]
	v_pk_fma_f32 v[16:17], v[16:17], v[104:105], v[200:201]
	v_pk_fma_f32 v[18:19], v[18:19], v[106:107], v[202:203]
	v_pk_mul_f32 v[176:177], v[28:29], v[28:29]
	v_pk_fma_f32 v[176:177], v[30:31], v[30:31], v[176:177]
	v_pk_fma_f32 v[176:177], v[24:25], v[24:25], v[176:177]
	v_pk_fma_f32 v[176:177], v[26:27], v[26:27], v[176:177]
	v_pk_fma_f32 v[176:177], v[20:21], v[20:21], v[176:177]
	v_pk_fma_f32 v[176:177], v[22:23], v[22:23], v[176:177]
	v_pk_fma_f32 v[176:177], v[16:17], v[16:17], v[176:177]
	v_pk_fma_f32 v[176:177], v[18:19], v[18:19], v[176:177]
	v_add_f32_e32 v210, v176, v177
	s_waitcnt vmcnt(0)
	v_pk_fma_f32 v[12:13], v[12:13], v[120:121], v[214:215]
	v_pk_fma_f32 v[14:15], v[14:15], v[122:123], v[216:217]
	v_pk_fma_f32 v[8:9], v[8:9], v[112:113], v[218:219]
	v_pk_fma_f32 v[10:11], v[10:11], v[114:115], v[220:221]
	v_pk_fma_f32 v[4:5], v[4:5], v[108:109], v[222:223]
	v_pk_fma_f32 v[6:7], v[6:7], v[110:111], v[224:225]
	v_pk_fma_f32 v[0:1], v[0:1], v[104:105], v[226:227]
	v_pk_fma_f32 v[2:3], v[2:3], v[106:107], v[228:229]
	v_pk_mul_f32 v[176:177], v[12:13], v[12:13]
	v_pk_fma_f32 v[176:177], v[14:15], v[14:15], v[176:177]
	v_pk_fma_f32 v[176:177], v[8:9], v[8:9], v[176:177]
	v_pk_fma_f32 v[176:177], v[10:11], v[10:11], v[176:177]
	v_pk_fma_f32 v[176:177], v[4:5], v[4:5], v[176:177]
	v_pk_fma_f32 v[176:177], v[6:7], v[6:7], v[176:177]
	v_pk_fma_f32 v[176:177], v[0:1], v[0:1], v[176:177]
	v_pk_fma_f32 v[176:177], v[2:3], v[2:3], v[176:177]
	v_add_f32_e32 v211, v176, v177
	ds_bpermute_b32 v246, v186, v204
	ds_bpermute_b32 v247, v186, v205
	ds_bpermute_b32 v248, v186, v206
	ds_bpermute_b32 v249, v186, v207
	ds_bpermute_b32 v250, v186, v208
	ds_bpermute_b32 v251, v186, v209
	ds_bpermute_b32 v252, v186, v210
	ds_bpermute_b32 v253, v186, v211
	s_waitcnt lgkmcnt(0)
;     __device__ __forceinline__ void operator()(AccRef acc, const Unit& u, int wr, int wc, int fr, int fq) const {
;     ...
;                     ss += __shfl_xor(ss, 16); ss += __shfl_xor(ss, 32);
;                     if (fq == 0) rowss[(size_t)row * 32 + u.pn * 4 + wc] = ss; } }
; __device__ __forceinline__ void final_rows(int gw, int lane, const f16* xo, float* out, const float* fg, const float* rowss) {
;     ...
;         for (int rr = 0; rr < 4; ++rr) { part[rr] = lane < 32 ? rowss[(size_t)(r0 + rr) * 32 + lane] : 0.f;
; #pragma unroll
;             for (int j = 0; j < 4; ++j) v[rr][j] = *(const u32x4*)(xo + (size_t)(r0 + rr) * D + 512 * j + 8 * lane); }
;         __builtin_amdgcn_sched_barrier(0);
; #pragma unroll
;         for (int rr = 0; rr < 4; ++rr) { const float rstd = rsqrtf(wave_sum(part[rr]) * (1.f / D) + EPS); float* rp = out + (size_t)(r0 + rr) * D + 8 * lane;
	v_pk_add_f32 v[204:205], v[204:205], v[246:247]
	v_pk_add_f32 v[206:207], v[206:207], v[248:249]
	v_pk_add_f32 v[208:209], v[208:209], v[250:251]
	v_pk_add_f32 v[210:211], v[210:211], v[252:253]
	ds_bpermute_b32 v246, v185, v204
	ds_bpermute_b32 v247, v185, v205
	ds_bpermute_b32 v248, v185, v206
	ds_bpermute_b32 v249, v185, v207
	ds_bpermute_b32 v250, v185, v208
	ds_bpermute_b32 v251, v185, v209
	ds_bpermute_b32 v252, v185, v210
	ds_bpermute_b32 v253, v185, v211
	s_waitcnt lgkmcnt(0)
	v_pk_add_f32 v[204:205], v[204:205], v[246:247]
	v_pk_add_f32 v[206:207], v[206:207], v[248:249]
	v_pk_add_f32 v[208:209], v[208:209], v[250:251]
	v_pk_add_f32 v[210:211], v[210:211], v[252:253]
	s_and_saveexec_b64 s[20:21], s[2:3]
	s_mov_b64 s[90:91], s[88:89]
	global_store_dword v187, v204, s[90:91] sc0 sc1
	s_add_u32 s90, s88, 0x800
	s_addc_u32 s91, s89, 0
	global_store_dword v187, v205, s[90:91] sc0 sc1
	s_add_u32 s90, s88, 0x1000
	s_addc_u32 s91, s89, 0
	global_store_dword v187, v206, s[90:91] sc0 sc1
	s_add_u32 s90, s88, 0x1800
	s_addc_u32 s91, s89, 0
	global_store_dword v187, v207, s[90:91] sc0 sc1
	s_add_u32 s90, s88, 0x4000
	s_addc_u32 s91, s89, 0
	global_store_dword v187, v208, s[90:91] sc0 sc1
	s_add_u32 s90, s88, 0x4800
	s_addc_u32 s91, s89, 0
	global_store_dword v187, v209, s[90:91] sc0 sc1
	s_add_u32 s90, s88, 0x5000
	s_addc_u32 s91, s89, 0
	global_store_dword v187, v210, s[90:91] sc0 sc1
	s_add_u32 s90, s88, 0x5800
	s_addc_u32 s91, s89, 0
	global_store_dword v187, v211, s[90:91] sc0 sc1
	s_or_b64 exec, exec, s[20:21]
	s_waitcnt vmcnt(0)
	s_barrier
	s_lshr_b32 s18, s65, 10
	s_cmp_lg_u32 s18, 0
	s_cbranch_scc1 .Lepi_skip
	s_lshl_b32 s18, s58, 6
	s_add_u32 s18, s18, 0xc000
	s_mov_b64 exec, 1
	v_mov_b32_e32 v175, s18
	v_mov_b32_e32 v255, 1
	global_atomic_add v175, v255, s[50:51]
	s_mov_b32 vcc_lo, 0
.Lepi_poll:
	s_sleep 1
	global_load_dword v255, v175, s[50:51] sc1
	s_add_u32 vcc_lo, vcc_lo, 1
	s_waitcnt vmcnt(0)
	v_readfirstlane_b32 s19, v255
	s_cmp_gt_u32 vcc_lo, 0x80000
	s_cbranch_scc1 .Lepi_polled
	s_cmp_lt_u32 s19, 8
	s_cbranch_scc1 .Lepi_poll
.Lepi_polled:
	buffer_inv sc1
	s_waitcnt vmcnt(0)
	s_mov_b64 exec, -1
.Lepi_skip:
	s_barrier
	s_mov_b64 s[90:91], s[26:27]
	global_load_dwordx4 v[188:191], v174, s[90:91]
	global_load_dwordx4 v[192:195], v174, s[90:91] offset:16
	s_add_u32 s90, s26, 0x800
	s_addc_u32 s91, s27, 0
	global_load_dwordx4 v[196:199], v174, s[90:91]
	global_load_dwordx4 v[200:203], v174, s[90:91] offset:16
	s_add_u32 s90, s26, 0x1000
	s_addc_u32 s91, s27, 0
	global_load_dwordx4 v[214:217], v174, s[90:91]
	global_load_dwordx4 v[218:221], v174, s[90:91] offset:16
	s_add_u32 s90, s26, 0x1800
	s_addc_u32 s91, s27, 0
	global_load_dwordx4 v[222:225], v174, s[90:91]
	global_load_dwordx4 v[226:229], v174, s[90:91] offset:16
	s_add_u32 s90, s26, 0x4000
	s_addc_u32 s91, s27, 0
	global_load_dwordx4 v[230:233], v174, s[90:91]
	global_load_dwordx4 v[234:237], v174, s[90:91] offset:16
	s_add_u32 s90, s26, 0x4800
	s_addc_u32 s91, s27, 0
	global_load_dwordx4 v[238:241], v174, s[90:91]
	global_load_dwordx4 v[242:245], v174, s[90:91] offset:16
	s_add_u32 s90, s26, 0x5000
	s_addc_u32 s91, s27, 0
	global_load_dwordx4 v[204:207], v174, s[90:91]
	global_load_dwordx4 v[208:211], v174, s[90:91] offset:16
	s_add_u32 s90, s26, 0x5800
	s_addc_u32 s91, s27, 0
	global_load_dwordx4 v[246:249], v174, s[90:91]
	global_load_dwordx4 v[250:253], v174, s[90:91] offset:16
	s_mov_b32 s18, 0x3a000000
	s_mov_b32 s19, 0x358637bd
	s_mov_b64 s[82:83], s[48:49]
	s_waitcnt vmcnt(14)
	v_pk_add_f32 v[188:189], v[188:189], v[190:191]
	v_pk_add_f32 v[192:193], v[192:193], v[194:195]
	v_pk_add_f32 v[188:189], v[188:189], v[192:193]
	v_add_f32_e32 v188, v188, v189
	s_waitcnt vmcnt(12)
	v_pk_add_f32 v[196:197], v[196:197], v[198:199]
	v_pk_add_f32 v[200:201], v[200:201], v[202:203]
	v_pk_add_f32 v[196:197], v[196:197], v[200:201]
	v_add_f32_e32 v196, v196, v197
	s_waitcnt vmcnt(10)
	v_pk_add_f32 v[214:215], v[214:215], v[216:217]
	v_pk_add_f32 v[218:219], v[218:219], v[220:221]
	v_pk_add_f32 v[214:215], v[214:215], v[218:219]
	v_add_f32_e32 v214, v214, v215
	s_waitcnt vmcnt(8)
	v_pk_add_f32 v[222:223], v[222:223], v[224:225]
	v_pk_add_f32 v[226:227], v[226:227], v[228:229]
	v_pk_add_f32 v[222:223], v[222:223], v[226:227]
	v_add_f32_e32 v222, v222, v223
	s_waitcnt vmcnt(6)
	v_pk_add_f32 v[230:231], v[230:231], v[232:233]
	v_pk_add_f32 v[234:235], v[234:235], v[236:237]
	v_pk_add_f32 v[230:231], v[230:231], v[234:235]
	v_add_f32_e32 v230, v230, v231
	s_waitcnt vmcnt(4)
	v_pk_add_f32 v[238:239], v[238:239], v[240:241]
	v_pk_add_f32 v[242:243], v[242:243], v[244:245]
	v_pk_add_f32 v[238:239], v[238:239], v[242:243]
	v_add_f32_e32 v238, v238, v239
	s_waitcnt vmcnt(2)
	v_pk_add_f32 v[204:205], v[204:205], v[206:207]
	v_pk_add_f32 v[208:209], v[208:209], v[210:211]
	v_pk_add_f32 v[204:205], v[204:205], v[208:209]
	v_add_f32_e32 v204, v204, v205
	s_waitcnt vmcnt(0)
	v_pk_add_f32 v[246:247], v[246:247], v[248:249]
	v_pk_add_f32 v[250:251], v[250:251], v[252:253]
	v_pk_add_f32 v[246:247], v[246:247], v[250:251]
	v_add_f32_e32 v246, v246, v247
	ds_bpermute_b32 v104, v186, v188
	ds_bpermute_b32 v105, v186, v196
	ds_bpermute_b32 v106, v186, v214
	ds_bpermute_b32 v107, v186, v222
	ds_bpermute_b32 v108, v186, v230
	ds_bpermute_b32 v109, v186, v238
	ds_bpermute_b32 v110, v186, v204
	ds_bpermute_b32 v111, v186, v246
	s_waitcnt lgkmcnt(0)
; __device__ __forceinline__ void unpack8h(const u32x4 w, f32x4& v0, f32x4& v1) { v0 = (f32x4){h16lo(w.x), h16hi(w.x), h16lo(w.y), h16hi(w.y)}; v1 = (f32x4){h16lo(w.z), h16hi(w.z), h16lo(w.w), h16hi(w.w)}; }
; __device__ __forceinline__ void final_rows(int gw, int lane, const f16* xo, float* out, const float* fg, const float* rowss) {
;     ...
;         for (int rr = 0; rr < 4; ++rr) { const float rstd = rsqrtf(wave_sum(part[rr]) * (1.f / D) + EPS); float* rp = out + (size_t)(r0 + rr) * D + 8 * lane;
; #pragma unroll
;             for (int j = 0; j < 4; ++j) { f32x4 a0, a1; unpack8h(v[rr][j], a0, a1); *(f32x4*)(rp + 512 * j) = a0 * rstd * g4[j][0]; *(f32x4*)(rp + 512 * j + 4) = a1 * rstd * g4[j][1]; } }
	v_add_f32_e32 v188, v188, v104
	v_add_f32_e32 v196, v196, v105
	v_add_f32_e32 v214, v214, v106
	v_add_f32_e32 v222, v222, v107
	v_add_f32_e32 v230, v230, v108
	v_add_f32_e32 v238, v238, v109
	v_add_f32_e32 v204, v204, v110
	v_add_f32_e32 v246, v246, v111
	ds_bpermute_b32 v104, v185, v188
	ds_bpermute_b32 v105, v185, v196
	ds_bpermute_b32 v106, v185, v214
	ds_bpermute_b32 v107, v185, v222
	ds_bpermute_b32 v108, v185, v230
	ds_bpermute_b32 v109, v185, v238
	ds_bpermute_b32 v110, v185, v204
	ds_bpermute_b32 v111, v185, v246
	s_waitcnt lgkmcnt(0)
	v_add_f32_e32 v188, v188, v104
	v_add_f32_e32 v196, v196, v105
	v_add_f32_e32 v214, v214, v106
	v_add_f32_e32 v222, v222, v107
	v_add_f32_e32 v230, v230, v108
	v_add_f32_e32 v238, v238, v109
	v_add_f32_e32 v204, v204, v110
	v_add_f32_e32 v246, v246, v111
	v_mov_b32_e32 v104, s19
	v_mov_b32_e32 v105, s19
	v_mov_b32_e32 v106, s19
	v_mov_b32_e32 v107, s19
	v_mov_b32_e32 v108, s19
	v_mov_b32_e32 v109, s19
	v_mov_b32_e32 v110, s19
	v_mov_b32_e32 v111, s19
	v_fmac_f32_e32 v104, s18, v188
	v_fmac_f32_e32 v105, s18, v196
	v_fmac_f32_e32 v106, s18, v214
	v_fmac_f32_e32 v107, s18, v222
	v_fmac_f32_e32 v108, s18, v230
	v_fmac_f32_e32 v109, s18, v238
	v_fmac_f32_e32 v110, s18, v204
	v_fmac_f32_e32 v111, s18, v246
	v_rsq_f32_e32 v188, v104
	v_rsq_f32_e32 v196, v105
	v_rsq_f32_e32 v214, v106
	v_rsq_f32_e32 v222, v107
	v_rsq_f32_e32 v230, v108
	v_rsq_f32_e32 v238, v109
	v_rsq_f32_e32 v204, v110
	v_rsq_f32_e32 v246, v111
	s_nop 1
	s_mov_b64 s[86:87], s[82:83]
	v_pk_mul_f32 v[140:141], v[140:141], v[188:189] op_sel_hi:[1,0]
	v_pk_mul_f32 v[142:143], v[142:143], v[188:189] op_sel_hi:[1,0]
	v_pk_mul_f32 v[140:141], v[140:141], v[144:145]
	v_pk_mul_f32 v[142:143], v[142:143], v[146:147]
	v_pk_mul_f32 v[136:137], v[136:137], v[188:189] op_sel_hi:[1,0]
	v_pk_mul_f32 v[138:139], v[138:139], v[188:189] op_sel_hi:[1,0]
	v_pk_mul_f32 v[136:137], v[136:137], v[148:149]
	v_pk_mul_f32 v[138:139], v[138:139], v[150:151]
	v_pk_mul_f32 v[132:133], v[132:133], v[188:189] op_sel_hi:[1,0]
	v_pk_mul_f32 v[134:135], v[134:135], v[188:189] op_sel_hi:[1,0]
	v_pk_mul_f32 v[132:133], v[132:133], v[152:153]
	v_pk_mul_f32 v[134:135], v[134:135], v[154:155]
	v_pk_mul_f32 v[128:129], v[128:129], v[188:189] op_sel_hi:[1,0]
	v_pk_mul_f32 v[130:131], v[130:131], v[188:189] op_sel_hi:[1,0]
	v_pk_mul_f32 v[128:129], v[128:129], v[156:157]
	v_pk_mul_f32 v[130:131], v[130:131], v[158:159]
	global_store_dwordx4 v173, v[140:143], s[86:87]
	global_store_dwordx4 v173, v[136:139], s[86:87] offset:16
	global_store_dwordx4 v173, v[132:135], s[86:87] offset:512
	global_store_dwordx4 v173, v[128:131], s[86:87] offset:528
	s_add_u32 s86, s82, 0x20000
	s_addc_u32 s87, s83, 0
	v_pk_mul_f32 v[124:125], v[124:125], v[196:197] op_sel_hi:[1,0]
	v_pk_mul_f32 v[126:127], v[126:127], v[196:197] op_sel_hi:[1,0]
	v_pk_mul_f32 v[124:125], v[124:125], v[144:145]
	v_pk_mul_f32 v[126:127], v[126:127], v[146:147]
	v_pk_mul_f32 v[116:117], v[116:117], v[196:197] op_sel_hi:[1,0]
	v_pk_mul_f32 v[118:119], v[118:119], v[196:197] op_sel_hi:[1,0]
	v_pk_mul_f32 v[116:117], v[116:117], v[148:149]
	v_pk_mul_f32 v[118:119], v[118:119], v[150:151]
	v_pk_mul_f32 v[100:101], v[100:101], v[196:197] op_sel_hi:[1,0]
	v_pk_mul_f32 v[102:103], v[102:103], v[196:197] op_sel_hi:[1,0]
	v_pk_mul_f32 v[100:101], v[100:101], v[152:153]
	v_pk_mul_f32 v[102:103], v[102:103], v[154:155]
	v_pk_mul_f32 v[96:97], v[96:97], v[196:197] op_sel_hi:[1,0]
	v_pk_mul_f32 v[98:99], v[98:99], v[196:197] op_sel_hi:[1,0]
	v_pk_mul_f32 v[96:97], v[96:97], v[156:157]
	v_pk_mul_f32 v[98:99], v[98:99], v[158:159]
	global_store_dwordx4 v173, v[124:127], s[86:87]
	global_store_dwordx4 v173, v[116:119], s[86:87] offset:16
	global_store_dwordx4 v173, v[100:103], s[86:87] offset:512
	global_store_dwordx4 v173, v[96:99], s[86:87] offset:528
	s_add_u32 s86, s82, 0x40000
	s_addc_u32 s87, s83, 0
	v_pk_mul_f32 v[92:93], v[92:93], v[214:215] op_sel_hi:[1,0]
	v_pk_mul_f32 v[94:95], v[94:95], v[214:215] op_sel_hi:[1,0]
	v_pk_mul_f32 v[92:93], v[92:93], v[144:145]
	v_pk_mul_f32 v[94:95], v[94:95], v[146:147]
	v_pk_mul_f32 v[88:89], v[88:89], v[214:215] op_sel_hi:[1,0]
	v_pk_mul_f32 v[90:91], v[90:91], v[214:215] op_sel_hi:[1,0]
	v_pk_mul_f32 v[88:89], v[88:89], v[148:149]
	v_pk_mul_f32 v[90:91], v[90:91], v[150:151]
	v_pk_mul_f32 v[84:85], v[84:85], v[214:215] op_sel_hi:[1,0]
	v_pk_mul_f32 v[86:87], v[86:87], v[214:215] op_sel_hi:[1,0]
	v_pk_mul_f32 v[84:85], v[84:85], v[152:153]
	v_pk_mul_f32 v[86:87], v[86:87], v[154:155]
	v_pk_mul_f32 v[80:81], v[80:81], v[214:215] op_sel_hi:[1,0]
	v_pk_mul_f32 v[82:83], v[82:83], v[214:215] op_sel_hi:[1,0]
	v_pk_mul_f32 v[80:81], v[80:81], v[156:157]
	v_pk_mul_f32 v[82:83], v[82:83], v[158:159]
	global_store_dwordx4 v173, v[92:95], s[86:87]
	global_store_dwordx4 v173, v[88:91], s[86:87] offset:16
	global_store_dwordx4 v173, v[84:87], s[86:87] offset:512
	global_store_dwordx4 v173, v[80:83], s[86:87] offset:528
	s_add_u32 s86, s82, 0x60000
	s_addc_u32 s87, s83, 0
	v_pk_mul_f32 v[76:77], v[76:77], v[222:223] op_sel_hi:[1,0]
	v_pk_mul_f32 v[78:79], v[78:79], v[222:223] op_sel_hi:[1,0]
	v_pk_mul_f32 v[76:77], v[76:77], v[144:145]
	v_pk_mul_f32 v[78:79], v[78:79], v[146:147]
	v_pk_mul_f32 v[72:73], v[72:73], v[222:223] op_sel_hi:[1,0]
	v_pk_mul_f32 v[74:75], v[74:75], v[222:223] op_sel_hi:[1,0]
; __device__ __forceinline__ void unpack8h(const u32x4 w, f32x4& v0, f32x4& v1) { v0 = (f32x4){h16lo(w.x), h16hi(w.x), h16lo(w.y), h16hi(w.y)}; v1 = (f32x4){h16lo(w.z), h16hi(w.z), h16lo(w.w), h16hi(w.w)}; }
; __device__ __forceinline__ void final_rows(int gw, int lane, const f16* xo, float* out, const float* fg, const float* rowss) {
;     ...
;         for (int rr = 0; rr < 4; ++rr) { const float rstd = rsqrtf(wave_sum(part[rr]) * (1.f / D) + EPS); float* rp = out + (size_t)(r0 + rr) * D + 8 * lane;
; #pragma unroll
;             for (int j = 0; j < 4; ++j) { f32x4 a0, a1; unpack8h(v[rr][j], a0, a1); *(f32x4*)(rp + 512 * j) = a0 * rstd * g4[j][0]; *(f32x4*)(rp + 512 * j + 4) = a1 * rstd * g4[j][1]; } }
	v_pk_mul_f32 v[72:73], v[72:73], v[148:149]
	v_pk_mul_f32 v[74:75], v[74:75], v[150:151]
	v_pk_mul_f32 v[68:69], v[68:69], v[222:223] op_sel_hi:[1,0]
	v_pk_mul_f32 v[70:71], v[70:71], v[222:223] op_sel_hi:[1,0]
	v_pk_mul_f32 v[68:69], v[68:69], v[152:153]
	v_pk_mul_f32 v[70:71], v[70:71], v[154:155]
	v_pk_mul_f32 v[64:65], v[64:65], v[222:223] op_sel_hi:[1,0]
	v_pk_mul_f32 v[66:67], v[66:67], v[222:223] op_sel_hi:[1,0]
	v_pk_mul_f32 v[64:65], v[64:65], v[156:157]
	v_pk_mul_f32 v[66:67], v[66:67], v[158:159]
	global_store_dwordx4 v173, v[76:79], s[86:87]
	global_store_dwordx4 v173, v[72:75], s[86:87] offset:16
	global_store_dwordx4 v173, v[68:71], s[86:87] offset:512
	global_store_dwordx4 v173, v[64:67], s[86:87] offset:528
	s_add_u32 s86, s82, 0x100000
	s_addc_u32 s87, s83, 0
	v_pk_mul_f32 v[60:61], v[60:61], v[230:231] op_sel_hi:[1,0]
	v_pk_mul_f32 v[62:63], v[62:63], v[230:231] op_sel_hi:[1,0]
	v_pk_mul_f32 v[60:61], v[60:61], v[144:145]
	v_pk_mul_f32 v[62:63], v[62:63], v[146:147]
	v_pk_mul_f32 v[56:57], v[56:57], v[230:231] op_sel_hi:[1,0]
	v_pk_mul_f32 v[58:59], v[58:59], v[230:231] op_sel_hi:[1,0]
	v_pk_mul_f32 v[56:57], v[56:57], v[148:149]
	v_pk_mul_f32 v[58:59], v[58:59], v[150:151]
	v_pk_mul_f32 v[52:53], v[52:53], v[230:231] op_sel_hi:[1,0]
	v_pk_mul_f32 v[54:55], v[54:55], v[230:231] op_sel_hi:[1,0]
	v_pk_mul_f32 v[52:53], v[52:53], v[152:153]
	v_pk_mul_f32 v[54:55], v[54:55], v[154:155]
	v_pk_mul_f32 v[48:49], v[48:49], v[230:231] op_sel_hi:[1,0]
	v_pk_mul_f32 v[50:51], v[50:51], v[230:231] op_sel_hi:[1,0]
	v_pk_mul_f32 v[48:49], v[48:49], v[156:157]
	v_pk_mul_f32 v[50:51], v[50:51], v[158:159]
	global_store_dwordx4 v173, v[60:63], s[86:87]
	global_store_dwordx4 v173, v[56:59], s[86:87] offset:16
	global_store_dwordx4 v173, v[52:55], s[86:87] offset:512
	global_store_dwordx4 v173, v[48:51], s[86:87] offset:528
	s_add_u32 s86, s82, 0x120000
	s_addc_u32 s87, s83, 0
	v_pk_mul_f32 v[44:45], v[44:45], v[238:239] op_sel_hi:[1,0]
	v_pk_mul_f32 v[46:47], v[46:47], v[238:239] op_sel_hi:[1,0]
	v_pk_mul_f32 v[44:45], v[44:45], v[144:145]
	v_pk_mul_f32 v[46:47], v[46:47], v[146:147]
	v_pk_mul_f32 v[40:41], v[40:41], v[238:239] op_sel_hi:[1,0]
	v_pk_mul_f32 v[42:43], v[42:43], v[238:239] op_sel_hi:[1,0]
	v_pk_mul_f32 v[40:41], v[40:41], v[148:149]
	v_pk_mul_f32 v[42:43], v[42:43], v[150:151]
	v_pk_mul_f32 v[36:37], v[36:37], v[238:239] op_sel_hi:[1,0]
	v_pk_mul_f32 v[38:39], v[38:39], v[238:239] op_sel_hi:[1,0]
	v_pk_mul_f32 v[36:37], v[36:37], v[152:153]
	v_pk_mul_f32 v[38:39], v[38:39], v[154:155]
	v_pk_mul_f32 v[32:33], v[32:33], v[238:239] op_sel_hi:[1,0]
	v_pk_mul_f32 v[34:35], v[34:35], v[238:239] op_sel_hi:[1,0]
	v_pk_mul_f32 v[32:33], v[32:33], v[156:157]
	v_pk_mul_f32 v[34:35], v[34:35], v[158:159]
	global_store_dwordx4 v173, v[44:47], s[86:87]
	global_store_dwordx4 v173, v[40:43], s[86:87] offset:16
	global_store_dwordx4 v173, v[36:39], s[86:87] offset:512
	global_store_dwordx4 v173, v[32:35], s[86:87] offset:528
	s_add_u32 s86, s82, 0x140000
	s_addc_u32 s87, s83, 0
	v_pk_mul_f32 v[28:29], v[28:29], v[204:205] op_sel_hi:[1,0]
	v_pk_mul_f32 v[30:31], v[30:31], v[204:205] op_sel_hi:[1,0]
	v_pk_mul_f32 v[28:29], v[28:29], v[144:145]
	v_pk_mul_f32 v[30:31], v[30:31], v[146:147]
	v_pk_mul_f32 v[24:25], v[24:25], v[204:205] op_sel_hi:[1,0]
	v_pk_mul_f32 v[26:27], v[26:27], v[204:205] op_sel_hi:[1,0]
	v_pk_mul_f32 v[24:25], v[24:25], v[148:149]
	v_pk_mul_f32 v[26:27], v[26:27], v[150:151]
	v_pk_mul_f32 v[20:21], v[20:21], v[204:205] op_sel_hi:[1,0]
	v_pk_mul_f32 v[22:23], v[22:23], v[204:205] op_sel_hi:[1,0]
	v_pk_mul_f32 v[20:21], v[20:21], v[152:153]
	v_pk_mul_f32 v[22:23], v[22:23], v[154:155]
	v_pk_mul_f32 v[16:17], v[16:17], v[204:205] op_sel_hi:[1,0]
	v_pk_mul_f32 v[18:19], v[18:19], v[204:205] op_sel_hi:[1,0]
	v_pk_mul_f32 v[16:17], v[16:17], v[156:157]
	v_pk_mul_f32 v[18:19], v[18:19], v[158:159]
	global_store_dwordx4 v173, v[28:31], s[86:87]
	global_store_dwordx4 v173, v[24:27], s[86:87] offset:16
	global_store_dwordx4 v173, v[20:23], s[86:87] offset:512
	global_store_dwordx4 v173, v[16:19], s[86:87] offset:528
	s_add_u32 s86, s82, 0x160000
	s_addc_u32 s87, s83, 0
	v_pk_mul_f32 v[12:13], v[12:13], v[246:247] op_sel_hi:[1,0]
	v_pk_mul_f32 v[14:15], v[14:15], v[246:247] op_sel_hi:[1,0]
	v_pk_mul_f32 v[12:13], v[12:13], v[144:145]
	v_pk_mul_f32 v[14:15], v[14:15], v[146:147]
	v_pk_mul_f32 v[8:9], v[8:9], v[246:247] op_sel_hi:[1,0]
	v_pk_mul_f32 v[10:11], v[10:11], v[246:247] op_sel_hi:[1,0]
	v_pk_mul_f32 v[8:9], v[8:9], v[148:149]
	v_pk_mul_f32 v[10:11], v[10:11], v[150:151]
	v_pk_mul_f32 v[4:5], v[4:5], v[246:247] op_sel_hi:[1,0]
	v_pk_mul_f32 v[6:7], v[6:7], v[246:247] op_sel_hi:[1,0]
	v_pk_mul_f32 v[4:5], v[4:5], v[152:153]
	v_pk_mul_f32 v[6:7], v[6:7], v[154:155]
	v_pk_mul_f32 v[0:1], v[0:1], v[246:247] op_sel_hi:[1,0]
	v_pk_mul_f32 v[2:3], v[2:3], v[246:247] op_sel_hi:[1,0]
	v_pk_mul_f32 v[0:1], v[0:1], v[156:157]
	v_pk_mul_f32 v[2:3], v[2:3], v[158:159]
	global_store_dwordx4 v173, v[12:15], s[86:87]
	global_store_dwordx4 v173, v[8:11], s[86:87] offset:16
	global_store_dwordx4 v173, v[4:7], s[86:87] offset:512
	global_store_dwordx4 v173, v[0:3], s[86:87] offset:528
	s_andn2_b64 vcc, exec, s[4:5]
	s_mov_b64 s[4:5], -1
	s_cbranch_vccnz .LBB0_1143
	s_andn2_b64 vcc, exec, s[14:15]
	s_cbranch_vccnz .LBB0_1142
	s_barrier
	s_branch .LBB0_1142

; __global__ void __launch_bounds__(NTHREADS, 2) mk_fwd(Args a) {
;     ...
;     PHASE(7,
;         pg8::DenseOrder S; S.init(M_LAT / 256, D / 256, G, bx, WGM_OUT);
;         EpiOut E{a.in[0], (f16*)(a.ws + WS_XO), (const float*)(a.ws + WS_MOD), (float*)(a.ws + WS_ROWSS)};
;         pg8::gemm_phase<CfgDense2048, EpiOut, pg8::DenseOrder, true, true>(lds, (const char*)(a.ws + WS_BRANCH), (const char*)(a.ws + WS_WOUT), S, E);
;     );
;     if (PROBE_PH == 8) tp0 = __builtin_amdgcn_s_memrealtime();
;     if (IN(8)) final_rows(vcu * NWAVES + wave, lane, (const f16*)(a.ws + WS_XO), a.out, a.in[21], (const float*)(a.ws + WS_ROWSS));
;     if (PROBE_PH == 8) { asm volatile("s_waitcnt vmcnt(0)" ::: "memory"); tp1 = __builtin_amdgcn_s_memrealtime(); }
.LBB0_1174:
.LBB0_1239:
	s_endpgm

; __global__ void __launch_bounds__(NTHREADS, 2) mk_fwd(Args a) {
	.amdhsa_kernel _Z6mk_fwd4Args
		.amdhsa_group_segment_fixed_size 0
		.amdhsa_private_segment_fixed_size 0
		.amdhsa_kernarg_size 456
		.amdhsa_user_sgpr_count 2
		.amdhsa_user_sgpr_dispatch_ptr 0
		.amdhsa_user_sgpr_queue_ptr 0
		.amdhsa_user_sgpr_kernarg_segment_ptr 1
		.amdhsa_user_sgpr_dispatch_id 0
		.amdhsa_user_sgpr_kernarg_preload_length 0
		.amdhsa_user_sgpr_kernarg_preload_offset 0
		.amdhsa_user_sgpr_private_segment_size 0
		.amdhsa_uses_dynamic_stack 0
		.amdhsa_enable_private_segment 0
		.amdhsa_system_sgpr_workgroup_id_x 1
		.amdhsa_system_sgpr_workgroup_id_y 0
		.amdhsa_system_sgpr_workgroup_id_z 0
		.amdhsa_system_sgpr_workgroup_info 0
		.amdhsa_system_vgpr_workitem_id 0
		.amdhsa_next_free_vgpr 256
		.amdhsa_next_free_sgpr 102
		.amdhsa_accum_offset 256
		.amdhsa_reserve_vcc 1
		.amdhsa_float_round_mode_32 0
		.amdhsa_float_round_mode_16_64 0
		.amdhsa_float_denorm_mode_32 3
		.amdhsa_float_denorm_mode_16_64 3
		.amdhsa_dx10_clamp 1
		.amdhsa_ieee_mode 1
		.amdhsa_fp16_overflow 0
		.amdhsa_tg_split 0
		.amdhsa_exception_fp_ieee_invalid_op 0
		.amdhsa_exception_fp_denorm_src 0
		.amdhsa_exception_fp_ieee_div_zero 0
		.amdhsa_exception_fp_ieee_overflow 0
		.amdhsa_exception_fp_ieee_underflow 0
		.amdhsa_exception_fp_ieee_inexact 0
		.amdhsa_exception_int_div_zero 0
	.end_amdhsa_kernel

; __global__ void __launch_bounds__(NTHREADS, 2) mk_fwd(Args a) {
amdhsa.kernels:
  - .agpr_count:     0
    .args:
      - .offset:         0
        .size:           200
        .value_kind:     by_value
      - .offset:         200
        .size:           4
        .value_kind:     hidden_block_count_x
      - .offset:         204
        .size:           4
        .value_kind:     hidden_block_count_y
      - .offset:         208
        .size:           4
        .value_kind:     hidden_block_count_z
      - .offset:         212
        .size:           2
        .value_kind:     hidden_group_size_x
      - .offset:         214
        .size:           2
        .value_kind:     hidden_group_size_y
      - .offset:         216
        .size:           2
        .value_kind:     hidden_group_size_z
      - .offset:         218
        .size:           2
        .value_kind:     hidden_remainder_x
      - .offset:         220
        .size:           2
        .value_kind:     hidden_remainder_y
      - .offset:         222
        .size:           2
        .value_kind:     hidden_remainder_z
      - .offset:         240
        .size:           8
        .value_kind:     hidden_global_offset_x
      - .offset:         248
        .size:           8
        .value_kind:     hidden_global_offset_y
      - .offset:         256
        .size:           8
        .value_kind:     hidden_global_offset_z
      - .offset:         264
        .size:           2
        .value_kind:     hidden_grid_dims
      - .offset:         320
        .size:           4
        .value_kind:     hidden_dynamic_lds_size
    .group_segment_fixed_size: 0
    .kernarg_segment_align: 8
    .kernarg_segment_size: 456
    .language:       OpenCL C
    .language_version:
      - 2
      - 0
    .max_flat_workgroup_size: 512
    .name:           _Z6mk_fwd4Args
    .private_segment_fixed_size: 0
    .sgpr_count:     108
    .sgpr_spill_count: 60
    .symbol:         _Z6mk_fwd4Args.kd
    .uniform_work_group_size: 1
    .uses_dynamic_stack: false
    .vgpr_count:     256
    .vgpr_spill_count: 0
    .wavefront_size: 64
